# GLA: q fragments kept in registers between the A-tile and output stages (8 fewer ds_read_b128 per wave per chunk)
# baseline (speedup 1.0000x reference)
; #define LAS __attribute__((address_space(3)))
; __device__ void gla_item(const Params& p, int item, LAS unsigned char* lds) {
;     ...
;         gla_wait(R, n2 == 0);
;         *(LAS u32x4*)(lds + qs + t * 272 + cgp * 32) = R.rq[0]; *(LAS u32x4*)(lds + qs + t * 272 + cgp * 32 + 16) = R.rq[1];
;         *(LAS u32x4*)(lds + KS + t * 272 + cgp * 32) = R.rk[0]; *(LAS u32x4*)(lds + KS + t * 272 + cgp * 32 + 16) = R.rk[1];
;         *(LAS u32x4*)(lds + vs + t * 144 + cgp * 16) = R.rv;
;         f32x4 dc; dc[0] = bflo(R.rdec.x); dc[1] = bfhi(R.rdec.x); dc[2] = bflo(R.rdec.y); dc[3] = bfhi(R.rdec.y);
;         asm volatile("" : "+v"(dc) :: "memory");
;         gla_load(R, (n + 2 < 64) ? n + 2 : 63, t, hq, hv, pdec);
;         LDS_BARRIER();
;         const unsigned kaddr = lbase + KS + (unsigned)((8 * g + (idx >> 2)) * 272 + (16 * w + 4 * (idx & 3)) * 2);
;         const unsigned vaddr = lbase + vs + (unsigned)((8 * g + (idx >> 2)) * 144 + (4 * (idx & 3)) * 2);
;         s16x4 k00, k01, k10, k11, a0, a1, a2, a3, b0, b1, b2, b3, c0, c1, c2, c3, d0, d1, d2, d3;
;         asm volatile(
;               "ds_read_b64_tr_b16 %0, %20\n\tds_read_b64_tr_b16 %1, %20 offset:1088\n\tds_read_b64_tr_b16 %2, %20 offset:8704\n\tds_read_b64_tr_b16 %3, %20 offset:9792\n\t"
;               "ds_read_b64_tr_b16 %4, %21\n\tds_read_b64_tr_b16 %5, %21 offset:32\n\tds_read_b64_tr_b16 %6, %21 offset:64\n\tds_read_b64_tr_b16 %7, %21 offset:96\n\t"
;               "ds_read_b64_tr_b16 %8, %21 offset:576\n\tds_read_b64_tr_b16 %9, %21 offset:608\n\tds_read_b64_tr_b16 %10, %21 offset:640\n\tds_read_b64_tr_b16 %11, %21 offset:672\n\t"
;               "ds_read_b64_tr_b16 %12, %21 offset:4608\n\tds_read_b64_tr_b16 %13, %21 offset:4640\n\tds_read_b64_tr_b16 %14, %21 offset:4672\n\tds_read_b64_tr_b16 %15, %21 offset:4704\n\t"
;               "ds_read_b64_tr_b16 %16, %21 offset:5184\n\tds_read_b64_tr_b16 %17, %21 offset:5216\n\tds_read_b64_tr_b16 %18, %21 offset:5248\n\tds_read_b64_tr_b16 %19, %21 offset:5280"
;               : "=&v"(k00), "=&v"(k01), "=&v"(k10), "=&v"(k11), "=&v"(a0), "=&v"(a1), "=&v"(a2), "=&v"(a3), "=&v"(b0), "=&v"(b1), "=&v"(b2), "=&v"(b3),
;                 "=&v"(c0), "=&v"(c1), "=&v"(c2), "=&v"(c3), "=&v"(d0), "=&v"(d1), "=&v"(d2), "=&v"(d3)
;               : "v"(kaddr), "v"(vaddr) : "memory");
;         { bf16x8 kf[4], qa[4], qb[4];
; #pragma unroll
.LBB0_114:
	s_add_i32 s2, s8, 1
	s_min_u32 s2, s2, 61
	s_lshl_b32 s2, s2, 6
	s_add_i32 s6, s2, 0x80
	ds_write_b128 v114, v[60:63] offset:17408
	ds_write_b128 v114, v[72:75] offset:17424
	ds_write_b128 v114, v[68:71] offset:34816
	ds_write_b128 v114, v[64:67] offset:34832
	ds_write_b128 v2, v[76:79] offset:61440
	v_lshlrev_b32_e32 v60, 16, v94
	v_and_b32_e32 v61, 0xffff0000, v94
	v_lshlrev_b32_e32 v62, 16, v95
	v_and_b32_e32 v63, 0xffff0000, v95
	v_add_u32_e32 v26, s6, v96
	s_movk_i32 s7, 0x3000
	s_lshl_b32 s18, s6, 10
	v_mad_i64_i32 v[36:37], s[2:3], v26, s7, v[80:81]
	v_lshl_add_u64 v[24:25], v[84:85], 0, s[18:19]
	v_lshl_add_u64 v[64:65], v[24:25], 0, s[12:13]
	v_mad_i64_i32 v[40:41], s[2:3], v26, s7, v[82:83]
	global_load_dwordx4 v[24:27], v[36:37], off
	v_lshl_add_u64 v[28:29], v[36:37], 0, 16
	global_load_dwordx4 v[28:31], v[28:29], off
	v_lshl_add_u64 v[32:33], v[36:37], 0, s[16:17]
	global_load_dwordx4 v[32:35], v[32:33], off
	v_lshl_add_u64 v[36:37], v[36:37], 0, s[22:23]
	global_load_dwordx4 v[36:39], v[36:37], off
	global_load_dwordx4 v[40:43], v[40:41], off
	global_load_dwordx2 v[90:91], v[64:65], off
	s_waitcnt lgkmcnt(0)
	s_barrier
	ds_read_b64_tr_b16 v[134:135], v97
	ds_read_b64_tr_b16 v[136:137], v97 offset:1088
	ds_read_b64_tr_b16 v[130:131], v97 offset:8704
	ds_read_b64_tr_b16 v[132:133], v97 offset:9792
	ds_read_b64_tr_b16 v[126:127], v103
	ds_read_b64_tr_b16 v[122:123], v103 offset:32
	ds_read_b64_tr_b16 v[118:119], v103 offset:64
	ds_read_b64_tr_b16 v[114:115], v103 offset:96
	ds_read_b64_tr_b16 v[128:129], v103 offset:576
	ds_read_b64_tr_b16 v[124:125], v103 offset:608
	ds_read_b64_tr_b16 v[120:121], v103 offset:640
	ds_read_b64_tr_b16 v[116:117], v103 offset:672
	ds_read_b64_tr_b16 v[76:77], v103 offset:4608
	ds_read_b64_tr_b16 v[72:73], v103 offset:4640
	ds_read_b64_tr_b16 v[68:69], v103 offset:4672
	ds_read_b64_tr_b16 v[64:65], v103 offset:4704
	ds_read_b64_tr_b16 v[78:79], v103 offset:5184
	ds_read_b64_tr_b16 v[74:75], v103 offset:5216
	ds_read_b64_tr_b16 v[70:71], v103 offset:5248
	ds_read_b64_tr_b16 v[66:67], v103 offset:5280
	ds_read_b128 v[138:141], v109 offset:34816
	ds_read_b128 v[168:171], v110 offset:17408
	ds_read_b128 v[172:175], v110 offset:21760
	ds_read_b128 v[150:153], v109 offset:34880
	s_waitcnt lgkmcnt(2)
	v_mfma_f32_16x16x32_bf16 v[142:145], v[138:141], v[168:171], 0
	s_add_i32 s2, s8, 2
	s_cmp_lt_u32 s8, 62
	s_mov_b32 s8, s2
	s_waitcnt lgkmcnt(1)
	v_mfma_f32_16x16x32_bf16 v[138:141], v[138:141], v[172:175], 0
	ds_read_b128 v[176:179], v110 offset:17472
	ds_read_b128 v[180:183], v110 offset:21824
	s_waitcnt lgkmcnt(1)
	v_mfma_f32_16x16x32_bf16 v[142:145], v[150:153], v[176:179], v[142:145]
	ds_read_b128 v[146:149], v109 offset:34944
	s_waitcnt lgkmcnt(1)
	v_mfma_f32_16x16x32_bf16 v[138:141], v[150:153], v[180:183], v[138:141]
	ds_read_b128 v[184:187], v110 offset:17536
	ds_read_b128 v[188:191], v110 offset:21888
	s_waitcnt lgkmcnt(1)
	v_mfma_f32_16x16x32_bf16 v[142:145], v[146:149], v[184:187], v[142:145]
	ds_read_b128 v[150:153], v109 offset:35008
	s_waitcnt lgkmcnt(1)
	v_mfma_f32_16x16x32_bf16 v[138:141], v[146:149], v[188:191], v[138:141]
	ds_read_b128 v[192:195], v110 offset:17600
	s_waitcnt lgkmcnt(0)
	v_mfma_f32_16x16x32_bf16 v[142:145], v[150:153], v[192:195], v[142:145]
	ds_read_b128 v[196:199], v110 offset:21952
	s_waitcnt lgkmcnt(0)
	s_nop 0
	v_mfma_f32_16x16x32_bf16 v[56:59], v[134:137], v[126:129], v[56:59]
	s_nop 4
	v_cndmask_b32_e64 v93, v142, 0, s[36:37]
	v_cndmask_b32_e64 v95, v145, 0, s[48:49]
	v_mfma_f32_16x16x32_bf16 v[52:55], v[134:137], v[122:125], v[52:55]
	v_mfma_f32_16x16x32_bf16 v[48:51], v[134:137], v[118:121], v[48:51]
	v_mfma_f32_16x16x32_bf16 v[44:47], v[134:137], v[114:117], v[44:47]
	v_mfma_f32_16x16x32_bf16 v[56:59], v[130:133], v[76:79], v[56:59]
	v_cndmask_b32_e64 v76, 0, v143, s[40:41]
	v_cndmask_b32_e64 v78, v144, 0, s[44:45]
	s_waitcnt lgkmcnt(0)
	v_mfma_f32_16x16x32_bf16 v[138:141], v[150:153], v[196:199], v[138:141]
	v_mfma_f32_16x16x32_bf16 v[52:55], v[130:133], v[72:75], v[52:55]
	s_nop 2
	v_mul_f32_e64 v58, v62, v58
	v_mul_f32_e64 v59, v63, v59
	v_pk_mul_f32 v[56:57], v[60:61], v[56:57]
	s_nop 0
	v_cndmask_b32_e64 v94, v138, 0, s[38:39]
	v_mfma_f32_16x16x32_bf16 v[48:51], v[130:133], v[68:71], v[48:51]
	v_cndmask_b32_e64 v77, 0, v139, s[42:43]
	v_cndmask_b32_e64 v79, v140, 0, s[46:47]
	v_cndmask_b32_e64 v122, v141, 0, s[50:51]
	v_mfma_f32_16x16x32_bf16 v[44:47], v[130:133], v[64:67], v[44:47]
	v_cvt_pk_bf16_f32 v72, v93, v76
	v_cvt_pk_bf16_f32 v73, v78, v95
	v_pk_mul_f32 v[54:55], v[62:63], v[54:55]
	v_pk_mul_f32 v[52:53], v[60:61], v[52:53]
	v_pk_mul_f32 v[48:49], v[60:61], v[48:49]
	s_nop 2
	v_pk_mul_f32 v[44:45], v[60:61], v[44:45]
	v_cvt_pk_bf16_f32 v60, v56, v57
	v_cvt_pk_bf16_f32 v61, v58, v59
	v_cvt_pk_bf16_f32 v74, v94, v77
	v_cvt_pk_bf16_f32 v75, v79, v122
	ds_write_b64 v113, v[72:73]
	ds_write_b64 v111, v[74:75]
	v_pk_mul_f32 v[50:51], v[62:63], v[50:51]
	ds_write_b64 v107, v[60:61]
	v_cvt_pk_bf16_f32 v60, v52, v53
	v_cvt_pk_bf16_f32 v61, v54, v55
	v_pk_mul_f32 v[46:47], v[62:63], v[46:47]
	ds_write_b64 v107, v[60:61] offset:4352
	v_cvt_pk_bf16_f32 v60, v48, v49
	v_cvt_pk_bf16_f32 v61, v50, v51
	ds_write_b64 v107, v[60:61] offset:8704
	v_cvt_pk_bf16_f32 v60, v44, v45
	v_cvt_pk_bf16_f32 v61, v46, v47
	ds_write_b64 v107, v[60:61] offset:13056
	s_waitcnt lgkmcnt(0)
	s_barrier
; __device__ __forceinline__ unsigned cvt_pk_bf16(float lo, float hi) { const f32x2v v = {lo, hi}; const b16x2v r = __builtin_convertvector(v, b16x2v); return __builtin_bit_cast(unsigned, r); }
; __device__ __forceinline__ f32x4 mfma16(bf16x8 a, bf16x8 b, f32x4 c) { return __builtin_amdgcn_mfma_f32_16x16x32_bf16(a, b, c, 0, 0, 0); }
; __device__ void gla_item(const Params& p, int item, LAS unsigned char* lds) {
;     ...
;         { const unsigned va = lbase + vs + (unsigned)((8 * g + (idx >> 2)) * 144 + (16 * jt + 4 * (idx & 3)) * 2);
;           s16x4 x0, x1, y0, y1;
;           asm volatile("ds_read_b64_tr_b16 %0, %4\n\tds_read_b64_tr_b16 %1, %4 offset:576\n\tds_read_b64_tr_b16 %2, %4 offset:4608\n\tds_read_b64_tr_b16 %3, %4 offset:5184"
;                        : "=&v"(x0), "=&v"(x1), "=&v"(y0), "=&v"(y1) : "v"(va) : "memory");
;           bf16x8 sf[4], qa[4], qb[4], a0f[2], a1f[2];
; #pragma unroll
;           for (int ks = 0; ks < 4; ++ks) { sf[ks] = frag_row(lds + stc, 272, 16 * jt, 32 * ks, idx, g); qa[ks] = frag_row(lds + qs, 272, 16 * it0, 32 * ks, idx, g); qb[ks] = frag_row(lds + qs, 272, 16 * it0 + 16, 32 * ks, idx, g); }
; #pragma unroll
;           for (int ks = 0; ks < 2; ++ks) { a0f[ks] = frag_row(lds + AS, 144, 16 * it0, 32 * ks, idx, g); a1f[ks] = frag_row(lds + AS, 144, 16 * it0 + 16, 32 * ks, idx, g); }
;           asm volatile("s_waitcnt lgkmcnt(0)" : "+v"(x0), "+v"(x1), "+v"(y0), "+v"(y1) :: "memory");
;           bf16x8 vf0, vf1;
;           MKF(vf0, x0, x1) MKF(vf1, y0, y1)
;           f32x4 oa = {0.f, 0.f, 0.f, 0.f}, ob = oa;
;           oa = mfma16(vf0, a0f[0], oa); ob = mfma16(vf0, a1f[0], ob); oa = mfma16(vf1, a0f[1], oa); ob = mfma16(vf1, a1f[1], ob);
; #pragma unroll
;           for (int ks = 0; ks < 4; ++ks) { oa = mfma16(sf[ks], qa[ks], oa); ob = mfma16(sf[ks], qb[ks], ob); }
;           u32x2 wa, wb; wa.x = cvt_pk_bf16(oa[0], oa[1]); wa.y = cvt_pk_bf16(oa[2], oa[3]); wb.x = cvt_pk_bf16(ob[0], ob[1]); wb.y = cvt_pk_bf16(ob[2], ob[3]);
;           bf16_t* op = og + (size_t)(b * SEQ + n * 64 + 16 * it0 + idx) * 1024 + hh * 256 + sl * 64 + 16 * jt + 4 * g;
;           *(u32x2*)op = wa; *(u32x2*)(op + 16 * 1024) = wb; }
	ds_read_b64_tr_b16 v[64:65], v104
	ds_read_b64_tr_b16 v[66:67], v104 offset:576
	ds_read_b64_tr_b16 v[60:61], v104 offset:4608
	ds_read_b64_tr_b16 v[62:63], v104 offset:5184
	ds_read_b128 v[68:71], v108
	ds_read_b128 v[72:75], v108 offset:64
	ds_read_b128 v[126:129], v108 offset:128
	ds_read_b128 v[130:133], v108 offset:192
	ds_read_b128 v[150:153], v112
	ds_read_b128 v[154:157], v112 offset:64
	ds_read_b128 v[158:161], v112 offset:2304
	ds_read_b128 v[162:165], v112 offset:2368
	s_waitcnt lgkmcnt(0)
	s_waitcnt lgkmcnt(3)
	v_mfma_f32_16x16x32_bf16 v[150:153], v[64:67], v[150:153], 0
	s_waitcnt lgkmcnt(1)
	v_mfma_f32_16x16x32_bf16 v[64:67], v[64:67], v[158:161], 0
	v_mfma_f32_16x16x32_bf16 v[150:153], v[60:63], v[154:157], v[150:153]
	s_waitcnt lgkmcnt(0)
	v_mfma_f32_16x16x32_bf16 v[60:63], v[60:63], v[162:165], v[64:67]
	v_mfma_f32_16x16x32_bf16 v[60:63], v[68:71], v[172:175], v[60:63]
	v_mfma_f32_16x16x32_bf16 v[64:67], v[68:71], v[168:171], v[150:153]
	v_mfma_f32_16x16x32_bf16 v[60:63], v[72:75], v[180:183], v[60:63]
	v_mfma_f32_16x16x32_bf16 v[64:67], v[72:75], v[176:179], v[64:67]
	v_mfma_f32_16x16x32_bf16 v[60:63], v[126:129], v[188:191], v[60:63]
	v_mfma_f32_16x16x32_bf16 v[64:67], v[126:129], v[184:187], v[64:67]
	v_mfma_f32_16x16x32_bf16 v[60:63], v[130:133], v[196:199], v[60:63]
	v_mfma_f32_16x16x32_bf16 v[64:67], v[130:133], v[192:195], v[64:67]
	s_nop 6
	v_cvt_pk_bf16_f32 v60, v60, v61
	v_cvt_pk_bf16_f32 v61, v62, v63
	v_add_u32_e32 v62, 64, v92
	v_ashrrev_i32_e32 v63, 31, v62
	v_lshlrev_b64 v[62:63], 11, v[62:63]
	v_cvt_pk_bf16_f32 v64, v64, v65
	v_cvt_pk_bf16_f32 v65, v66, v67
	v_lshl_add_u64 v[62:63], v[88:89], 0, v[62:63]
	global_store_dwordx2 v[62:63], v[64:65], off
	v_add_co_u32_e32 v62, vcc, 0x8000, v62
	v_add_u32_e32 v92, 0x80, v92
	s_nop 0
	v_addc_co_u32_e32 v63, vcc, 0, v63, vcc
	global_store_dwordx2 v[62:63], v[60:61], off
	s_cbranch_scc0 .LBB0_128

; #define LAS __attribute__((address_space(3)))
; __device__ void gla_item(const Params& p, int item, LAS unsigned char* lds) {
;     ...
;         gla_wait(R, n2 == 0);
;         *(LAS u32x4*)(lds + qs + t * 272 + cgp * 32) = R.rq[0]; *(LAS u32x4*)(lds + qs + t * 272 + cgp * 32 + 16) = R.rq[1];
;         *(LAS u32x4*)(lds + KS + t * 272 + cgp * 32) = R.rk[0]; *(LAS u32x4*)(lds + KS + t * 272 + cgp * 32 + 16) = R.rk[1];
;         *(LAS u32x4*)(lds + vs + t * 144 + cgp * 16) = R.rv;
;         f32x4 dc; dc[0] = bflo(R.rdec.x); dc[1] = bfhi(R.rdec.x); dc[2] = bflo(R.rdec.y); dc[3] = bfhi(R.rdec.y);
;         asm volatile("" : "+v"(dc) :: "memory");
;         gla_load(R, (n + 2 < 64) ? n + 2 : 63, t, hq, hv, pdec);
;         LDS_BARRIER();
;         const unsigned kaddr = lbase + KS + (unsigned)((8 * g + (idx >> 2)) * 272 + (16 * w + 4 * (idx & 3)) * 2);
;         const unsigned vaddr = lbase + vs + (unsigned)((8 * g + (idx >> 2)) * 144 + (4 * (idx & 3)) * 2);
;         s16x4 k00, k01, k10, k11, a0, a1, a2, a3, b0, b1, b2, b3, c0, c1, c2, c3, d0, d1, d2, d3;
;         asm volatile(
;               "ds_read_b64_tr_b16 %0, %20\n\tds_read_b64_tr_b16 %1, %20 offset:1088\n\tds_read_b64_tr_b16 %2, %20 offset:8704\n\tds_read_b64_tr_b16 %3, %20 offset:9792\n\t"
;               "ds_read_b64_tr_b16 %4, %21\n\tds_read_b64_tr_b16 %5, %21 offset:32\n\tds_read_b64_tr_b16 %6, %21 offset:64\n\tds_read_b64_tr_b16 %7, %21 offset:96\n\t"
;               "ds_read_b64_tr_b16 %8, %21 offset:576\n\tds_read_b64_tr_b16 %9, %21 offset:608\n\tds_read_b64_tr_b16 %10, %21 offset:640\n\tds_read_b64_tr_b16 %11, %21 offset:672\n\t"
;               "ds_read_b64_tr_b16 %12, %21 offset:4608\n\tds_read_b64_tr_b16 %13, %21 offset:4640\n\tds_read_b64_tr_b16 %14, %21 offset:4672\n\tds_read_b64_tr_b16 %15, %21 offset:4704\n\t"
;               "ds_read_b64_tr_b16 %16, %21 offset:5184\n\tds_read_b64_tr_b16 %17, %21 offset:5216\n\tds_read_b64_tr_b16 %18, %21 offset:5248\n\tds_read_b64_tr_b16 %19, %21 offset:5280"
;               : "=&v"(k00), "=&v"(k01), "=&v"(k10), "=&v"(k11), "=&v"(a0), "=&v"(a1), "=&v"(a2), "=&v"(a3), "=&v"(b0), "=&v"(b1), "=&v"(b2), "=&v"(b3),
;                 "=&v"(c0), "=&v"(c1), "=&v"(c2), "=&v"(c3), "=&v"(d0), "=&v"(d1), "=&v"(d2), "=&v"(d3)
;               : "v"(kaddr), "v"(vaddr) : "memory");
;         { bf16x8 kf[4], qa[4], qb[4];
; #pragma unroll
.LBB0_118:
	s_min_u32 s6, s8, 61
	s_lshl_b32 s6, s6, 6
	v_add_u32_e32 v114, v1, v0
	s_add_i32 s9, s6, 0x80
	ds_write_b128 v114, v[64:67]
	ds_write_b128 v114, v[60:63] offset:16
	ds_write_b128 v114, v[76:79] offset:34816
	ds_write_b128 v114, v[72:75] offset:34832
	ds_write_b128 v2, v[68:71] offset:52224
	v_lshlrev_b32_e32 v60, 16, v94
	v_and_b32_e32 v61, 0xffff0000, v94
	v_lshlrev_b32_e32 v62, 16, v95
	v_and_b32_e32 v63, 0xffff0000, v95
	v_add_u32_e32 v6, s9, v96
	s_movk_i32 s10, 0x3000
	s_lshl_b32 s18, s9, 10
	v_mad_i64_i32 v[16:17], s[6:7], v6, s10, v[80:81]
	v_lshl_add_u64 v[4:5], v[84:85], 0, s[18:19]
	v_lshl_add_u64 v[64:65], v[4:5], 0, s[12:13]
	v_mad_i64_i32 v[20:21], s[6:7], v6, s10, v[82:83]
	global_load_dwordx4 v[4:7], v[16:17], off
	v_lshl_add_u64 v[8:9], v[16:17], 0, 16
	global_load_dwordx4 v[8:11], v[8:9], off
	v_lshl_add_u64 v[12:13], v[16:17], 0, s[16:17]
	global_load_dwordx4 v[12:15], v[12:13], off
	v_lshl_add_u64 v[16:17], v[16:17], 0, s[22:23]
	global_load_dwordx4 v[16:19], v[16:17], off
	global_load_dwordx4 v[20:23], v[20:21], off
	global_load_dwordx2 v[86:87], v[64:65], off
	s_waitcnt lgkmcnt(0)
	s_barrier
	ds_read_b64_tr_b16 v[136:137], v97
	ds_read_b64_tr_b16 v[138:139], v97 offset:1088
	ds_read_b64_tr_b16 v[132:133], v97 offset:8704
	ds_read_b64_tr_b16 v[134:135], v97 offset:9792
	ds_read_b64_tr_b16 v[128:129], v101
	ds_read_b64_tr_b16 v[124:125], v101 offset:32
	ds_read_b64_tr_b16 v[120:121], v101 offset:64
	ds_read_b64_tr_b16 v[116:117], v101 offset:96
	ds_read_b64_tr_b16 v[130:131], v101 offset:576
	ds_read_b64_tr_b16 v[126:127], v101 offset:608
	ds_read_b64_tr_b16 v[122:123], v101 offset:640
	ds_read_b64_tr_b16 v[118:119], v101 offset:672
	ds_read_b64_tr_b16 v[76:77], v101 offset:4608
	ds_read_b64_tr_b16 v[72:73], v101 offset:4640
	ds_read_b64_tr_b16 v[68:69], v101 offset:4672
	ds_read_b64_tr_b16 v[64:65], v101 offset:4704
	ds_read_b64_tr_b16 v[78:79], v101 offset:5184
	ds_read_b64_tr_b16 v[74:75], v101 offset:5216
	ds_read_b64_tr_b16 v[70:71], v101 offset:5248
	ds_read_b64_tr_b16 v[66:67], v101 offset:5280
	ds_read_b128 v[140:143], v109 offset:34816
	ds_read_b128 v[168:171], v110
	ds_read_b128 v[148:151], v109 offset:34880
	ds_read_b128 v[172:175], v110 offset:64
	s_waitcnt lgkmcnt(0)
	v_mfma_f32_16x16x32_bf16 v[144:147], v[140:143], v[168:171], 0
	ds_read_b128 v[176:179], v110 offset:4352
	ds_read_b128 v[180:183], v110 offset:4416
	v_mfma_f32_16x16x32_bf16 v[144:147], v[148:151], v[172:175], v[144:147]
	ds_read_b128 v[152:155], v109 offset:34944
	s_waitcnt lgkmcnt(2)
	v_mfma_f32_16x16x32_bf16 v[140:143], v[140:143], v[176:179], 0
	s_waitcnt lgkmcnt(1)
	v_mfma_f32_16x16x32_bf16 v[140:143], v[148:151], v[180:183], v[140:143]
	ds_read_b128 v[184:187], v110 offset:128
	ds_read_b128 v[156:159], v109 offset:35008
	ds_read_b128 v[188:191], v110 offset:192
	s_waitcnt lgkmcnt(2)
	v_mfma_f32_16x16x32_bf16 v[144:147], v[152:155], v[184:187], v[144:147]
	ds_read_b128 v[192:195], v110 offset:4480
	ds_read_b128 v[196:199], v110 offset:4544
	s_waitcnt lgkmcnt(0)
	s_waitcnt lgkmcnt(1)
	v_mfma_f32_16x16x32_bf16 v[140:143], v[152:155], v[192:195], v[140:143]
	v_mfma_f32_16x16x32_bf16 v[56:59], v[136:139], v[128:131], v[56:59]
	v_mfma_f32_16x16x32_bf16 v[52:55], v[136:139], v[124:127], v[52:55]
	v_mfma_f32_16x16x32_bf16 v[48:51], v[136:139], v[120:123], v[48:51]
	v_mfma_f32_16x16x32_bf16 v[44:47], v[136:139], v[116:119], v[44:47]
	v_mfma_f32_16x16x32_bf16 v[144:147], v[156:159], v[188:191], v[144:147]
	s_waitcnt lgkmcnt(0)
	v_mfma_f32_16x16x32_bf16 v[140:143], v[156:159], v[196:199], v[140:143]
	v_mfma_f32_16x16x32_bf16 v[56:59], v[132:135], v[76:79], v[56:59]
	s_nop 4
	v_cndmask_b32_e64 v93, v144, 0, s[36:37]
	v_cndmask_b32_e64 v95, 0, v145, s[40:41]
	v_cndmask_b32_e64 v77, v146, 0, s[44:45]
	v_mfma_f32_16x16x32_bf16 v[52:55], v[132:135], v[72:75], v[52:55]
	v_cndmask_b32_e64 v79, v142, 0, s[46:47]
	v_cndmask_b32_e64 v112, v147, 0, s[48:49]
	v_cndmask_b32_e64 v113, v143, 0, s[50:51]
	v_mfma_f32_16x16x32_bf16 v[48:51], v[132:135], v[68:71], v[48:51]
	v_mul_f32_e64 v58, v62, v58
	v_mul_f32_e64 v59, v63, v59
	v_pk_mul_f32 v[56:57], v[60:61], v[56:57]
	v_cndmask_b32_e64 v94, v140, 0, s[38:39]
	v_mfma_f32_16x16x32_bf16 v[44:47], v[132:135], v[64:67], v[44:47]
	v_cndmask_b32_e64 v78, 0, v141, s[42:43]
	v_cvt_pk_bf16_f32 v76, v93, v95
	v_cvt_pk_bf16_f32 v77, v77, v112
	v_cvt_pk_bf16_f32 v73, v79, v113
	v_add_u32_e32 v113, v99, v100
	v_pk_mul_f32 v[54:55], v[62:63], v[54:55]
	v_pk_mul_f32 v[52:53], v[60:61], v[52:53]
	v_pk_mul_f32 v[48:49], v[60:61], v[48:49]
	v_pk_mul_f32 v[44:45], v[60:61], v[44:45]
	v_cvt_pk_bf16_f32 v60, v56, v57
	v_cvt_pk_bf16_f32 v61, v58, v59
	v_cvt_pk_bf16_f32 v72, v94, v78
	ds_write_b64 v113, v[76:77]
	ds_write_b64 v111, v[72:73]
	v_pk_mul_f32 v[50:51], v[62:63], v[50:51]
	ds_write_b64 v105, v[60:61]
	v_cvt_pk_bf16_f32 v60, v52, v53
	v_cvt_pk_bf16_f32 v61, v54, v55
	v_pk_mul_f32 v[46:47], v[62:63], v[46:47]
	ds_write_b64 v105, v[60:61] offset:4352
	v_cvt_pk_bf16_f32 v60, v48, v49
	v_cvt_pk_bf16_f32 v61, v50, v51
	ds_write_b64 v105, v[60:61] offset:8704
	v_cvt_pk_bf16_f32 v60, v44, v45
	v_cvt_pk_bf16_f32 v61, v46, v47
	ds_write_b64 v105, v[60:61] offset:13056
	s_waitcnt lgkmcnt(0)
	s_barrier
; #define LAS __attribute__((address_space(3)))
; __device__ void gla_item(const Params& p, int item, LAS unsigned char* lds) {
;     ...
;     for (int n2 = 0; n2 < 64; n2 += 2) {
; #pragma unroll
;       for (int par = 0; par < 2; ++par) {
;         const int n = n2 + par;
;         GlaRegs& R = par ? RB : RA;
;         const int qs = QS0 + par * 17408, vs = VS0 + par * 9216, stc = ST0 + par * 17408, stn = ST0 + (par ^ 1) * 17408;
;         gla_wait(R, n2 == 0);
;         *(LAS u32x4*)(lds + qs + t * 272 + cgp * 32) = R.rq[0]; *(LAS u32x4*)(lds + qs + t * 272 + cgp * 32 + 16) = R.rq[1];
;     ...
;         { const unsigned va = lbase + vs + (unsigned)((8 * g + (idx >> 2)) * 144 + (16 * jt + 4 * (idx & 3)) * 2);
;           s16x4 x0, x1, y0, y1;
;           asm volatile("ds_read_b64_tr_b16 %0, %4\n\tds_read_b64_tr_b16 %1, %4 offset:576\n\tds_read_b64_tr_b16 %2, %4 offset:4608\n\tds_read_b64_tr_b16 %3, %4 offset:5184"
;                        : "=&v"(x0), "=&v"(x1), "=&v"(y0), "=&v"(y1) : "v"(va) : "memory");
;           bf16x8 sf[4], qa[4], qb[4], a0f[2], a1f[2];
; #pragma unroll
;           for (int ks = 0; ks < 4; ++ks) { sf[ks] = frag_row(lds + stc, 272, 16 * jt, 32 * ks, idx, g); qa[ks] = frag_row(lds + qs, 272, 16 * it0, 32 * ks, idx, g); qb[ks] = frag_row(lds + qs, 272, 16 * it0 + 16, 32 * ks, idx, g); }
; #pragma unroll
;           for (int ks = 0; ks < 2; ++ks) { a0f[ks] = frag_row(lds + AS, 144, 16 * it0, 32 * ks, idx, g); a1f[ks] = frag_row(lds + AS, 144, 16 * it0 + 16, 32 * ks, idx, g); }
;           asm volatile("s_waitcnt lgkmcnt(0)" : "+v"(x0), "+v"(x1), "+v"(y0), "+v"(y1) :: "memory");
;           bf16x8 vf0, vf1;
;           MKF(vf0, x0, x1) MKF(vf1, y0, y1)
;           f32x4 oa = {0.f, 0.f, 0.f, 0.f}, ob = oa;
;           oa = mfma16(vf0, a0f[0], oa); ob = mfma16(vf0, a1f[0], ob); oa = mfma16(vf1, a0f[1], oa); ob = mfma16(vf1, a1f[1], ob);
; #pragma unroll
;           for (int ks = 0; ks < 4; ++ks) { oa = mfma16(sf[ks], qa[ks], oa); ob = mfma16(sf[ks], qb[ks], ob); }
;           u32x2 wa, wb; wa.x = cvt_pk_bf16(oa[0], oa[1]); wa.y = cvt_pk_bf16(oa[2], oa[3]); wb.x = cvt_pk_bf16(ob[0], ob[1]); wb.y = cvt_pk_bf16(ob[2], ob[3]);
;           bf16_t* op = og + (size_t)(b * SEQ + n * 64 + 16 * it0 + idx) * 1024 + hh * 256 + sl * 64 + 16 * jt + 4 * g;
;           *(u32x2*)op = wa; *(u32x2*)(op + 16 * 1024) = wb; }
	ds_read_b64_tr_b16 v[64:65], v102
	ds_read_b64_tr_b16 v[66:67], v102 offset:576
	ds_read_b64_tr_b16 v[60:61], v102 offset:4608
	ds_read_b64_tr_b16 v[62:63], v102 offset:5184
	v_add_u32_e32 v112, v99, v98
	ds_read_b128 v[68:71], v106
	ds_read_b128 v[72:75], v106 offset:64
	ds_read_b128 v[128:131], v106 offset:128
	ds_read_b128 v[132:135], v106 offset:192
	ds_read_b128 v[152:155], v112
	ds_read_b128 v[156:159], v112 offset:64
	ds_read_b128 v[160:163], v112 offset:2304
	ds_read_b128 v[164:167], v112 offset:2368
	s_waitcnt lgkmcnt(0)
	v_ashrrev_i32_e32 v93, 31, v92
	s_waitcnt lgkmcnt(3)
	v_mfma_f32_16x16x32_bf16 v[152:155], v[64:67], v[152:155], 0
	s_waitcnt lgkmcnt(1)
	v_mfma_f32_16x16x32_bf16 v[64:67], v[64:67], v[160:163], 0
	v_mfma_f32_16x16x32_bf16 v[152:155], v[60:63], v[156:159], v[152:155]
	s_waitcnt lgkmcnt(0)
	v_mfma_f32_16x16x32_bf16 v[60:63], v[60:63], v[164:167], v[64:67]
	v_mfma_f32_16x16x32_bf16 v[60:63], v[68:71], v[176:179], v[60:63]
	v_mfma_f32_16x16x32_bf16 v[64:67], v[68:71], v[168:171], v[152:155]
	v_mfma_f32_16x16x32_bf16 v[60:63], v[72:75], v[180:183], v[60:63]
	v_mfma_f32_16x16x32_bf16 v[64:67], v[72:75], v[172:175], v[64:67]
	v_mfma_f32_16x16x32_bf16 v[60:63], v[128:131], v[192:195], v[60:63]
	v_mfma_f32_16x16x32_bf16 v[64:67], v[128:131], v[184:187], v[64:67]
	v_mfma_f32_16x16x32_bf16 v[60:63], v[132:135], v[196:199], v[60:63]
	v_mfma_f32_16x16x32_bf16 v[64:67], v[132:135], v[188:191], v[64:67]
	s_nop 6
	v_cvt_pk_bf16_f32 v60, v60, v61
	v_cvt_pk_bf16_f32 v61, v62, v63
	v_lshlrev_b64 v[62:63], 11, v[92:93]
	v_cvt_pk_bf16_f32 v64, v64, v65
	v_cvt_pk_bf16_f32 v65, v66, v67
	v_lshl_add_u64 v[62:63], v[88:89], 0, v[62:63]
	global_store_dwordx2 v[62:63], v[64:65], off
	v_add_co_u32_e32 v62, vcc, 0x8000, v62
	s_nop 1
	v_addc_co_u32_e32 v63, vcc, 0, v63, vcc
	s_andn2_b64 vcc, exec, s[2:3]
	global_store_dwordx2 v[62:63], v[60:61], off
	s_cbranch_vccnz .LBB0_121
	v_mov_b64_e32 v[66:67], v[38:39]
	v_mov_b64_e32 v[62:63], v[26:27]
	v_mov_b64_e32 v[70:71], v[34:35]
	v_mov_b64_e32 v[78:79], v[42:43]
	v_mov_b64_e32 v[74:75], v[30:31]
	v_mov_b64_e32 v[64:65], v[36:37]
	v_mov_b64_e32 v[94:95], v[90:91]
	v_mov_b64_e32 v[60:61], v[24:25]
	v_mov_b64_e32 v[68:69], v[32:33]
	v_mov_b64_e32 v[76:77], v[40:41]
	v_mov_b64_e32 v[72:73], v[28:29]
	s_waitcnt vmcnt(10)
	s_cbranch_execnz .LBB0_114
	s_branch .LBB0_122
